# P7->P8 grid seam made XCD-local (P8 reads only MERGED rows produced by workgroups of the same XCD, like the FFN-in->FFN-out seam)
# speedup vs baseline: 1.0098x; 1.0098x over previous
.LBB0_1776:
	s_andn2_saveexec_b64 s[14:15], s[14:15]
	s_cbranch_execz .LBB0_1799
	s_mov_b64 s[14:15], exec
	buffer_wbl2 sc1
	s_waitcnt lgkmcnt(0)
	s_waitcnt vmcnt(0)
	s_branch .Lseam7_local
	v_mbcnt_lo_u32_b32 v1, s14, 0
	v_mbcnt_hi_u32_b32 v1, s15, v1
	v_cmp_eq_u32_e32 vcc, 0, v1
	s_and_saveexec_b64 s[24:25], vcc
	s_cbranch_execz .LBB0_1779
	s_bcnt1_i32_b64 s14, s[14:15]
	v_mov_b32_e32 v2, s14
	global_atomic_add v2, v224, v2, s[10:11] offset:1024 sc0
